# win loop: add-zero seeds of the running softmax sums dropped (bit-identical), on top of the scalar sub flag
# baseline (speedup 1.0000x reference)
.LBB0_828:
	s_nop 1
	v_exp_f32_e32 v80, v80
	v_exp_f32_e32 v81, v81
	v_exp_f32_e32 v82, v82
	v_exp_f32_e32 v83, v83
	v_exp_f32_e32 v84, v84
	v_exp_f32_e32 v85, v85
	v_exp_f32_e32 v86, v86
	v_exp_f32_e32 v87, v87
	v_pk_add_f32 v[242:243], v[80:81], v[82:83]
	v_exp_f32_e32 v88, v88
	v_exp_f32_e32 v89, v89
	s_nop 0
	v_exp_f32_e32 v90, v90
	v_exp_f32_e32 v91, v91
	v_pk_add_f32 v[242:243], v[84:85], v[242:243]
	v_exp_f32_e32 v92, v92
	v_exp_f32_e32 v93, v93
	v_exp_f32_e32 v64, v64
	v_exp_f32_e32 v65, v65
	v_pk_add_f32 v[242:243], v[86:87], v[242:243]
	v_exp_f32_e32 v94, v94
	v_exp_f32_e32 v95, v95
	v_exp_f32_e32 v66, v66
	v_exp_f32_e32 v67, v67
	v_cvt_pk_bf16_f32 v80, v80, v81
	v_cvt_pk_bf16_f32 v81, v82, v83
	v_cvt_pk_bf16_f32 v82, v84, v85
	v_pk_add_f32 v[84:85], v[88:89], v[242:243]
	v_exp_f32_e32 v68, v68
	v_pk_add_f32 v[84:85], v[90:91], v[84:85]
	v_exp_f32_e32 v69, v69
	v_cvt_pk_bf16_f32 v83, v86, v87
	v_pk_add_f32 v[84:85], v[92:93], v[84:85]
	s_waitcnt vmcnt(3)
	v_mfma_f32_32x32x16_bf16 v[32:47], v[156:159], v[80:83], v[32:47]
	v_exp_f32_e32 v70, v70
	v_exp_f32_e32 v71, v71
	v_pk_add_f32 v[242:243], v[94:95], v[84:85]
	v_cvt_pk_bf16_f32 v84, v88, v89
	v_cvt_pk_bf16_f32 v85, v90, v91
	v_cvt_pk_bf16_f32 v86, v92, v93
	v_cvt_pk_bf16_f32 v87, v94, v95
	s_waitcnt vmcnt(2)
	v_mfma_f32_32x32x16_bf16 v[48:63], v[152:155], v[80:83], v[48:63]
	v_pk_add_f32 v[80:81], v[64:65], v[66:67]
	s_nop 0
	v_cvt_pk_bf16_f32 v64, v64, v65
	v_cvt_pk_bf16_f32 v65, v66, v67
	v_exp_f32_e32 v72, v72
	s_nop 0
	v_cvt_pk_bf16_f32 v66, v68, v69
	v_cvt_pk_bf16_f32 v67, v70, v71
	v_exp_f32_e32 v73, v73
	v_mfma_f32_32x32x16_bf16 v[16:31], v[156:159], v[64:67], v[16:31]
	v_add_f32_e64 v80, v68, v80
	v_add_f32_e64 v81, v69, v81
	v_exp_f32_e32 v68, v74
	v_exp_f32_e32 v69, v75
	v_pk_add_f32 v[80:81], v[70:71], v[80:81]
	v_exp_f32_e32 v70, v76
	v_exp_f32_e32 v71, v77
	v_exp_f32_e32 v74, v78
	v_mfma_f32_32x32x16_bf16 v[0:15], v[152:155], v[64:67], v[0:15]
	v_exp_f32_e32 v75, v79
	v_pk_add_f32 v[80:81], v[72:73], v[80:81]
	v_mov_b32_e32 v78, v242
	v_pk_add_f32 v[76:77], v[68:69], v[80:81]
	s_andn2_b64 vcc, exec, s[8:9]
	v_pk_add_f32 v[64:65], v[70:71], v[76:77]
	s_waitcnt vmcnt(1)
	v_mfma_f32_32x32x16_bf16 v[32:47], v[148:151], v[84:87], v[32:47]
	v_add_f32_e64 v76, v74, v64
	v_add_f32_e64 v77, v75, v65
	v_cvt_pk_bf16_f32 v64, v72, v73
	v_cvt_pk_bf16_f32 v65, v68, v69
	v_cvt_pk_bf16_f32 v66, v70, v71
	v_cvt_pk_bf16_f32 v67, v74, v75
	v_mov_b32_e32 v79, v76
	s_waitcnt vmcnt(0)
	v_mfma_f32_32x32x16_bf16 v[48:63], v[144:147], v[84:87], v[48:63]
	v_mov_b32_e32 v76, v243
	v_add_f32_e64 v68, v78, v76
	v_add_f32_e64 v69, v79, v77
	v_add_f32_e64 v162, v162, v68
	v_add_f32_e64 v163, v163, v69
	v_mfma_f32_32x32x16_bf16 v[16:31], v[148:151], v[64:67], v[16:31]
	v_mfma_f32_32x32x16_bf16 v[0:15], v[144:147], v[64:67], v[0:15]
	s_cbranch_vccz .LBB0_778
	s_mov_b32 s12, s20
	s_mov_b32 s21, s17
	s_branch .LBB0_821
